# sub 2: local-state items 960..1023 moved to workgroups 192..255 (one each) so workgroups 0..191 run 5 items instead of 5-6
# baseline (speedup 1.0000x reference)
; __global__ void __launch_bounds__(512) mega_fwd(Params p) {
;     ...
;             if (bx < 192) for (int it = bx; it < 1024; it += 192) { if (it < 512) mlstm_local(B, it, lds); else ret_local(B, it - 512, lds); }
.LBB0_464:
	v_readlane_b32 s0, v254, 4
	v_readlane_b32 s1, v254, 5
	s_cmpk_lt_i32 s0, 0xc0
	s_cbranch_scc1 .LBB0_472
	s_addk_i32 s0, 0x300
	s_branch .LBB0_472

; __global__ void __launch_bounds__(512) mega_fwd(Params p) {
;     ...
;             if (bx < 192) for (int it = bx; it < 1024; it += 192) { if (it < 512) mlstm_local(B, it, lds); else ret_local(B, it - 512, lds); }
.LBB0_471:
	s_add_i32 s0, s26, 0xc0
	s_cmpk_gt_i32 s26, 0x2ff
	s_waitcnt lgkmcnt(0)
	s_cbranch_scc1 .LBB0_465
